# plus_hgscan_lds_staged_decay
# baseline (speedup 1.0000x reference)
.LBB0_995:
	s_waitcnt vmcnt(0)
	v_mov_b32_e32 v119, v181
	s_ashr_i32 s12, s69, 4
	v_lshlrev_b32_e32 v78, 2, v119
	v_and_b32_e32 v118, 0x7c, v78
	s_and_b32 s8, s69, 15
	v_lshlrev_b32_e32 v115, 2, v118
	v_lshl_add_u32 v114, s8, 10, v78
	v_lshlrev_b32_e32 v114, 1, v114
	s_lshl_b32 s13, s12, 22
	s_add_u32 s0, s4, s13
	s_addc_u32 s1, s5, 0
	s_add_u32 s16, s0, 0x80000
	s_addc_u32 s17, s1, 0
	s_lshl_b32 s13, s12, 16
	s_add_u32 s24, s6, s13
	s_addc_u32 s25, s7, 0
	s_mov_b64 s[30:31], s[0:1]
	v_lshlrev_b32_e32 v116, 4, v119
	s_barrier
	global_load_dwordx4 v[32:35], v116, s[24:25]
	v_add_u32_e32 v117, 0x1000, v116
	global_load_dwordx4 v[36:39], v117, s[24:25]
	v_add_u32_e32 v117, 0x2000, v116
	global_load_dwordx4 v[40:43], v117, s[24:25]
	v_add_u32_e32 v117, 0x3000, v116
	global_load_dwordx4 v[44:47], v117, s[24:25]
	v_add_u32_e32 v117, 0x4000, v116
	global_load_dwordx4 v[48:51], v117, s[24:25]
	v_add_u32_e32 v117, 0x5000, v116
	global_load_dwordx4 v[52:55], v117, s[24:25]
	v_add_u32_e32 v117, 0x6000, v116
	global_load_dwordx4 v[56:59], v117, s[24:25]
	v_add_u32_e32 v117, 0x7000, v116
	global_load_dwordx4 v[60:63], v117, s[24:25]
	v_add_u32_e32 v117, 0x8000, v116
	global_load_dwordx4 v[64:67], v117, s[24:25]
	v_add_u32_e32 v117, 0x9000, v116
	global_load_dwordx4 v[68:71], v117, s[24:25]
	v_add_u32_e32 v117, 0xa000, v116
	global_load_dwordx4 v[78:81], v117, s[24:25]
	v_add_u32_e32 v117, 0xb000, v116
	global_load_dwordx4 v[82:85], v117, s[24:25]
	v_add_u32_e32 v117, 0xc000, v116
	global_load_dwordx4 v[86:89], v117, s[24:25]
	v_add_u32_e32 v117, 0xd000, v116
	global_load_dwordx4 v[90:93], v117, s[24:25]
	v_add_u32_e32 v117, 0xe000, v116
	global_load_dwordx4 v[94:97], v117, s[24:25]
	v_add_u32_e32 v117, 0xf000, v116
	global_load_dwordx4 v[98:101], v117, s[24:25]
	global_load_dwordx2 v[0:1], v114, s[30:31]
	s_add_u32 s30, s30, 0x8000
	s_addc_u32 s31, s31, 0
	global_load_dwordx2 v[2:3], v114, s[30:31]
	s_add_u32 s30, s30, 0x8000
	s_addc_u32 s31, s31, 0
	global_load_dwordx2 v[4:5], v114, s[30:31]
	s_add_u32 s30, s30, 0x8000
	s_addc_u32 s31, s31, 0
	global_load_dwordx2 v[6:7], v114, s[30:31]
	s_add_u32 s30, s30, 0x8000
	s_addc_u32 s31, s31, 0
	global_load_dwordx2 v[8:9], v114, s[30:31]
	s_add_u32 s30, s30, 0x8000
	s_addc_u32 s31, s31, 0
	global_load_dwordx2 v[10:11], v114, s[30:31]
	s_add_u32 s30, s30, 0x8000
	s_addc_u32 s31, s31, 0
	global_load_dwordx2 v[12:13], v114, s[30:31]
	s_add_u32 s30, s30, 0x8000
	s_addc_u32 s31, s31, 0
	global_load_dwordx2 v[14:15], v114, s[30:31]
	s_add_u32 s30, s30, 0x8000
	s_addc_u32 s31, s31, 0
	global_load_dwordx2 v[16:17], v114, s[30:31]
	s_add_u32 s30, s30, 0x8000
	s_addc_u32 s31, s31, 0
	global_load_dwordx2 v[18:19], v114, s[30:31]
	s_add_u32 s30, s30, 0x8000
	s_addc_u32 s31, s31, 0
	global_load_dwordx2 v[20:21], v114, s[30:31]
	s_add_u32 s30, s30, 0x8000
	s_addc_u32 s31, s31, 0
	global_load_dwordx2 v[22:23], v114, s[30:31]
	s_add_u32 s30, s30, 0x8000
	s_addc_u32 s31, s31, 0
	global_load_dwordx2 v[24:25], v114, s[30:31]
	s_add_u32 s30, s30, 0x8000
	s_addc_u32 s31, s31, 0
	global_load_dwordx2 v[26:27], v114, s[30:31]
	s_add_u32 s30, s30, 0x8000
	s_addc_u32 s31, s31, 0
	global_load_dwordx2 v[28:29], v114, s[30:31]
	s_add_u32 s30, s30, 0x8000
	s_addc_u32 s31, s31, 0
	global_load_dwordx2 v[30:31], v114, s[30:31]
	s_add_u32 s30, s30, 0x8000
	s_addc_u32 s31, s31, 0
	s_waitcnt vmcnt(16)
	ds_write_b128 v116, v[32:35]
	ds_write_b128 v116, v[36:39] offset:4096
	ds_write_b128 v116, v[40:43] offset:8192
	ds_write_b128 v116, v[44:47] offset:12288
	ds_write_b128 v116, v[48:51] offset:16384
	ds_write_b128 v116, v[52:55] offset:20480
	ds_write_b128 v116, v[56:59] offset:24576
	ds_write_b128 v116, v[60:63] offset:28672
	ds_write_b128 v116, v[64:67] offset:32768
	ds_write_b128 v116, v[68:71] offset:36864
	ds_write_b128 v116, v[78:81] offset:40960
	ds_write_b128 v116, v[82:85] offset:45056
	ds_write_b128 v116, v[86:89] offset:49152
	ds_write_b128 v116, v[90:93] offset:53248
	ds_write_b128 v116, v[94:97] offset:57344
	ds_write_b128 v116, v[98:101] offset:61440
	s_waitcnt lgkmcnt(0)
	s_barrier
	v_mov_b32_e32 v104, 0
	v_mov_b32_e32 v105, 0
	v_mov_b32_e32 v106, 0
	v_mov_b32_e32 v107, 0
	ds_read_b128 v[32:35], v115 offset:0
	ds_read_b128 v[36:39], v115 offset:512
	ds_read_b128 v[40:43], v115 offset:1024
	v_cvt_pk_bf16_f32 v112, v104, v105
	v_cvt_pk_bf16_f32 v113, v106, v107
	global_store_dwordx2 v114, v[112:113], s[0:1]
	ds_read_b128 v[44:47], v115 offset:1536
	s_waitcnt vmcnt(16) lgkmcnt(3)
	v_lshlrev_b32_e32 v108, 16, v0
	v_and_b32_e32 v109, 0xffff0000, v0
	v_lshlrev_b32_e32 v110, 16, v1
	v_and_b32_e32 v111, 0xffff0000, v1
	v_pk_fma_f32 v[104:105], v[32:33], v[104:105], v[108:109]
	v_pk_fma_f32 v[106:107], v[34:35], v[106:107], v[110:111]
	s_add_u32 s0, s0, 0x8000
	s_addc_u32 s1, s1, 0
	global_load_dwordx2 v[0:1], v114, s[16:17]
	s_add_u32 s16, s16, 0x8000
	s_addc_u32 s17, s17, 0
	v_cvt_pk_bf16_f32 v112, v104, v105
	v_cvt_pk_bf16_f32 v113, v106, v107
	global_store_dwordx2 v114, v[112:113], s[0:1]
	ds_read_b128 v[32:35], v115 offset:2048
	s_waitcnt vmcnt(17) lgkmcnt(3)
	v_lshlrev_b32_e32 v108, 16, v2
	v_and_b32_e32 v109, 0xffff0000, v2
	v_lshlrev_b32_e32 v110, 16, v3
	v_and_b32_e32 v111, 0xffff0000, v3
	v_pk_fma_f32 v[104:105], v[36:37], v[104:105], v[108:109]
	v_pk_fma_f32 v[106:107], v[38:39], v[106:107], v[110:111]
	s_add_u32 s0, s0, 0x8000
	s_addc_u32 s1, s1, 0
	global_load_dwordx2 v[2:3], v114, s[16:17]
	s_add_u32 s16, s16, 0x8000
	s_addc_u32 s17, s17, 0
	v_cvt_pk_bf16_f32 v112, v104, v105
	v_cvt_pk_bf16_f32 v113, v106, v107
	global_store_dwordx2 v114, v[112:113], s[0:1]
	ds_read_b128 v[36:39], v115 offset:2560
	s_waitcnt vmcnt(18) lgkmcnt(3)
	v_lshlrev_b32_e32 v108, 16, v4
	v_and_b32_e32 v109, 0xffff0000, v4
	v_lshlrev_b32_e32 v110, 16, v5
	v_and_b32_e32 v111, 0xffff0000, v5
	v_pk_fma_f32 v[104:105], v[40:41], v[104:105], v[108:109]
	v_pk_fma_f32 v[106:107], v[42:43], v[106:107], v[110:111]
	s_add_u32 s0, s0, 0x8000
	s_addc_u32 s1, s1, 0
	global_load_dwordx2 v[4:5], v114, s[16:17]
	s_add_u32 s16, s16, 0x8000
	s_addc_u32 s17, s17, 0
	v_cvt_pk_bf16_f32 v112, v104, v105
	v_cvt_pk_bf16_f32 v113, v106, v107
	global_store_dwordx2 v114, v[112:113], s[0:1]
	ds_read_b128 v[40:43], v115 offset:3072
	s_waitcnt vmcnt(19) lgkmcnt(3)
	v_lshlrev_b32_e32 v108, 16, v6
	v_and_b32_e32 v109, 0xffff0000, v6
	v_lshlrev_b32_e32 v110, 16, v7
	v_and_b32_e32 v111, 0xffff0000, v7
	v_pk_fma_f32 v[104:105], v[44:45], v[104:105], v[108:109]
	v_pk_fma_f32 v[106:107], v[46:47], v[106:107], v[110:111]
	s_add_u32 s0, s0, 0x8000
	s_addc_u32 s1, s1, 0
	global_load_dwordx2 v[6:7], v114, s[16:17]
	s_add_u32 s16, s16, 0x8000
	s_addc_u32 s17, s17, 0
	v_cvt_pk_bf16_f32 v112, v104, v105
	v_cvt_pk_bf16_f32 v113, v106, v107
	global_store_dwordx2 v114, v[112:113], s[0:1]
	ds_read_b128 v[44:47], v115 offset:3584
	s_waitcnt vmcnt(20) lgkmcnt(3)
	v_lshlrev_b32_e32 v108, 16, v8
	v_and_b32_e32 v109, 0xffff0000, v8
	v_lshlrev_b32_e32 v110, 16, v9
	v_and_b32_e32 v111, 0xffff0000, v9
	v_pk_fma_f32 v[104:105], v[32:33], v[104:105], v[108:109]
	v_pk_fma_f32 v[106:107], v[34:35], v[106:107], v[110:111]
	s_add_u32 s0, s0, 0x8000
	s_addc_u32 s1, s1, 0
	global_load_dwordx2 v[8:9], v114, s[16:17]
	s_add_u32 s16, s16, 0x8000
	s_addc_u32 s17, s17, 0
	v_cvt_pk_bf16_f32 v112, v104, v105
	v_cvt_pk_bf16_f32 v113, v106, v107
	global_store_dwordx2 v114, v[112:113], s[0:1]
	ds_read_b128 v[32:35], v115 offset:4096
	s_waitcnt vmcnt(21) lgkmcnt(3)
	v_lshlrev_b32_e32 v108, 16, v10
	v_and_b32_e32 v109, 0xffff0000, v10
	v_lshlrev_b32_e32 v110, 16, v11
	v_and_b32_e32 v111, 0xffff0000, v11
	v_pk_fma_f32 v[104:105], v[36:37], v[104:105], v[108:109]
	v_pk_fma_f32 v[106:107], v[38:39], v[106:107], v[110:111]
	s_add_u32 s0, s0, 0x8000
	s_addc_u32 s1, s1, 0
	global_load_dwordx2 v[10:11], v114, s[16:17]
	s_add_u32 s16, s16, 0x8000
	s_addc_u32 s17, s17, 0
	v_cvt_pk_bf16_f32 v112, v104, v105
	v_cvt_pk_bf16_f32 v113, v106, v107
	global_store_dwordx2 v114, v[112:113], s[0:1]
	ds_read_b128 v[36:39], v115 offset:4608
	s_waitcnt vmcnt(22) lgkmcnt(3)
	v_lshlrev_b32_e32 v108, 16, v12
	v_and_b32_e32 v109, 0xffff0000, v12
	v_lshlrev_b32_e32 v110, 16, v13
	v_and_b32_e32 v111, 0xffff0000, v13
	v_pk_fma_f32 v[104:105], v[40:41], v[104:105], v[108:109]
	v_pk_fma_f32 v[106:107], v[42:43], v[106:107], v[110:111]
	s_add_u32 s0, s0, 0x8000
	s_addc_u32 s1, s1, 0
	global_load_dwordx2 v[12:13], v114, s[16:17]
	s_add_u32 s16, s16, 0x8000
	s_addc_u32 s17, s17, 0
	v_cvt_pk_bf16_f32 v112, v104, v105
	v_cvt_pk_bf16_f32 v113, v106, v107
	global_store_dwordx2 v114, v[112:113], s[0:1]
	ds_read_b128 v[40:43], v115 offset:5120
	s_waitcnt vmcnt(23) lgkmcnt(3)
	v_lshlrev_b32_e32 v108, 16, v14
	v_and_b32_e32 v109, 0xffff0000, v14
	v_lshlrev_b32_e32 v110, 16, v15
	v_and_b32_e32 v111, 0xffff0000, v15
	v_pk_fma_f32 v[104:105], v[44:45], v[104:105], v[108:109]
	v_pk_fma_f32 v[106:107], v[46:47], v[106:107], v[110:111]
	s_add_u32 s0, s0, 0x8000
	s_addc_u32 s1, s1, 0
	global_load_dwordx2 v[14:15], v114, s[16:17]
	s_add_u32 s16, s16, 0x8000
	s_addc_u32 s17, s17, 0
	v_cvt_pk_bf16_f32 v112, v104, v105
	v_cvt_pk_bf16_f32 v113, v106, v107
	global_store_dwordx2 v114, v[112:113], s[0:1]
	ds_read_b128 v[44:47], v115 offset:5632
	s_waitcnt vmcnt(24) lgkmcnt(3)
	v_lshlrev_b32_e32 v108, 16, v16
	v_and_b32_e32 v109, 0xffff0000, v16
	v_lshlrev_b32_e32 v110, 16, v17
	v_and_b32_e32 v111, 0xffff0000, v17
	v_pk_fma_f32 v[104:105], v[32:33], v[104:105], v[108:109]
	v_pk_fma_f32 v[106:107], v[34:35], v[106:107], v[110:111]
	s_add_u32 s0, s0, 0x8000
	s_addc_u32 s1, s1, 0
	global_load_dwordx2 v[16:17], v114, s[16:17]
	s_add_u32 s16, s16, 0x8000
	s_addc_u32 s17, s17, 0
	v_cvt_pk_bf16_f32 v112, v104, v105
	v_cvt_pk_bf16_f32 v113, v106, v107
	global_store_dwordx2 v114, v[112:113], s[0:1]
	ds_read_b128 v[32:35], v115 offset:6144
	s_waitcnt vmcnt(25) lgkmcnt(3)
	v_lshlrev_b32_e32 v108, 16, v18
	v_and_b32_e32 v109, 0xffff0000, v18
	v_lshlrev_b32_e32 v110, 16, v19
	v_and_b32_e32 v111, 0xffff0000, v19
	v_pk_fma_f32 v[104:105], v[36:37], v[104:105], v[108:109]
	v_pk_fma_f32 v[106:107], v[38:39], v[106:107], v[110:111]
	s_add_u32 s0, s0, 0x8000
	s_addc_u32 s1, s1, 0
	global_load_dwordx2 v[18:19], v114, s[16:17]
	s_add_u32 s16, s16, 0x8000
	s_addc_u32 s17, s17, 0
	v_cvt_pk_bf16_f32 v112, v104, v105
	v_cvt_pk_bf16_f32 v113, v106, v107
	global_store_dwordx2 v114, v[112:113], s[0:1]
	ds_read_b128 v[36:39], v115 offset:6656
	s_waitcnt vmcnt(26) lgkmcnt(3)
	v_lshlrev_b32_e32 v108, 16, v20
	v_and_b32_e32 v109, 0xffff0000, v20
	v_lshlrev_b32_e32 v110, 16, v21
	v_and_b32_e32 v111, 0xffff0000, v21
	v_pk_fma_f32 v[104:105], v[40:41], v[104:105], v[108:109]
	v_pk_fma_f32 v[106:107], v[42:43], v[106:107], v[110:111]
	s_add_u32 s0, s0, 0x8000
	s_addc_u32 s1, s1, 0
	global_load_dwordx2 v[20:21], v114, s[16:17]
	s_add_u32 s16, s16, 0x8000
	s_addc_u32 s17, s17, 0
	v_cvt_pk_bf16_f32 v112, v104, v105
	v_cvt_pk_bf16_f32 v113, v106, v107
	global_store_dwordx2 v114, v[112:113], s[0:1]
	ds_read_b128 v[40:43], v115 offset:7168
	s_waitcnt vmcnt(27) lgkmcnt(3)
	v_lshlrev_b32_e32 v108, 16, v22
	v_and_b32_e32 v109, 0xffff0000, v22
	v_lshlrev_b32_e32 v110, 16, v23
	v_and_b32_e32 v111, 0xffff0000, v23
	v_pk_fma_f32 v[104:105], v[44:45], v[104:105], v[108:109]
	v_pk_fma_f32 v[106:107], v[46:47], v[106:107], v[110:111]
	s_add_u32 s0, s0, 0x8000
	s_addc_u32 s1, s1, 0
	global_load_dwordx2 v[22:23], v114, s[16:17]
	s_add_u32 s16, s16, 0x8000
	s_addc_u32 s17, s17, 0
	v_cvt_pk_bf16_f32 v112, v104, v105
	v_cvt_pk_bf16_f32 v113, v106, v107
	global_store_dwordx2 v114, v[112:113], s[0:1]
	ds_read_b128 v[44:47], v115 offset:7680
	s_waitcnt vmcnt(28) lgkmcnt(3)
	v_lshlrev_b32_e32 v108, 16, v24
	v_and_b32_e32 v109, 0xffff0000, v24
	v_lshlrev_b32_e32 v110, 16, v25
	v_and_b32_e32 v111, 0xffff0000, v25
	v_pk_fma_f32 v[104:105], v[32:33], v[104:105], v[108:109]
	v_pk_fma_f32 v[106:107], v[34:35], v[106:107], v[110:111]
	s_add_u32 s0, s0, 0x8000
	s_addc_u32 s1, s1, 0
	global_load_dwordx2 v[24:25], v114, s[16:17]
	s_add_u32 s16, s16, 0x8000
	s_addc_u32 s17, s17, 0
	v_cvt_pk_bf16_f32 v112, v104, v105
	v_cvt_pk_bf16_f32 v113, v106, v107
	global_store_dwordx2 v114, v[112:113], s[0:1]
	ds_read_b128 v[32:35], v115 offset:8192
	s_waitcnt vmcnt(29) lgkmcnt(3)
	v_lshlrev_b32_e32 v108, 16, v26
	v_and_b32_e32 v109, 0xffff0000, v26
	v_lshlrev_b32_e32 v110, 16, v27
	v_and_b32_e32 v111, 0xffff0000, v27
	v_pk_fma_f32 v[104:105], v[36:37], v[104:105], v[108:109]
	v_pk_fma_f32 v[106:107], v[38:39], v[106:107], v[110:111]
	s_add_u32 s0, s0, 0x8000
	s_addc_u32 s1, s1, 0
	global_load_dwordx2 v[26:27], v114, s[16:17]
	s_add_u32 s16, s16, 0x8000
	s_addc_u32 s17, s17, 0
	v_cvt_pk_bf16_f32 v112, v104, v105
	v_cvt_pk_bf16_f32 v113, v106, v107
	global_store_dwordx2 v114, v[112:113], s[0:1]
	ds_read_b128 v[36:39], v115 offset:8704
	s_waitcnt vmcnt(30) lgkmcnt(3)
	v_lshlrev_b32_e32 v108, 16, v28
	v_and_b32_e32 v109, 0xffff0000, v28
	v_lshlrev_b32_e32 v110, 16, v29
	v_and_b32_e32 v111, 0xffff0000, v29
	v_pk_fma_f32 v[104:105], v[40:41], v[104:105], v[108:109]
	v_pk_fma_f32 v[106:107], v[42:43], v[106:107], v[110:111]
	s_add_u32 s0, s0, 0x8000
	s_addc_u32 s1, s1, 0
	global_load_dwordx2 v[28:29], v114, s[16:17]
	s_add_u32 s16, s16, 0x8000
	s_addc_u32 s17, s17, 0
	v_cvt_pk_bf16_f32 v112, v104, v105
	v_cvt_pk_bf16_f32 v113, v106, v107
	global_store_dwordx2 v114, v[112:113], s[0:1]
	ds_read_b128 v[40:43], v115 offset:9216
	s_waitcnt vmcnt(31) lgkmcnt(3)
	v_lshlrev_b32_e32 v108, 16, v30
	v_and_b32_e32 v109, 0xffff0000, v30
	v_lshlrev_b32_e32 v110, 16, v31
	v_and_b32_e32 v111, 0xffff0000, v31
	v_pk_fma_f32 v[104:105], v[44:45], v[104:105], v[108:109]
	v_pk_fma_f32 v[106:107], v[46:47], v[106:107], v[110:111]
	s_add_u32 s0, s0, 0x8000
	s_addc_u32 s1, s1, 0
	global_load_dwordx2 v[30:31], v114, s[16:17]
	s_add_u32 s16, s16, 0x8000
	s_addc_u32 s17, s17, 0
	v_add_u32_e32 v115, 0x2000, v115
	s_mov_b32 s13, 0
.Lhgs_loop:
	v_cvt_pk_bf16_f32 v112, v104, v105
	v_cvt_pk_bf16_f32 v113, v106, v107
	global_store_dwordx2 v114, v[112:113], s[0:1]
	ds_read_b128 v[44:47], v115 offset:1536
	s_waitcnt vmcnt(31) lgkmcnt(3)
	v_lshlrev_b32_e32 v108, 16, v0
	v_and_b32_e32 v109, 0xffff0000, v0
	v_lshlrev_b32_e32 v110, 16, v1
	v_and_b32_e32 v111, 0xffff0000, v1
	v_pk_fma_f32 v[104:105], v[32:33], v[104:105], v[108:109]
	v_pk_fma_f32 v[106:107], v[34:35], v[106:107], v[110:111]
	s_add_u32 s0, s0, 0x8000
	s_addc_u32 s1, s1, 0
	global_load_dwordx2 v[0:1], v114, s[16:17]
	s_add_u32 s16, s16, 0x8000
	s_addc_u32 s17, s17, 0
	v_cvt_pk_bf16_f32 v112, v104, v105
	v_cvt_pk_bf16_f32 v113, v106, v107
	global_store_dwordx2 v114, v[112:113], s[0:1]
	ds_read_b128 v[32:35], v115 offset:2048
	s_waitcnt vmcnt(31) lgkmcnt(3)
	v_lshlrev_b32_e32 v108, 16, v2
	v_and_b32_e32 v109, 0xffff0000, v2
	v_lshlrev_b32_e32 v110, 16, v3
	v_and_b32_e32 v111, 0xffff0000, v3
	v_pk_fma_f32 v[104:105], v[36:37], v[104:105], v[108:109]
	v_pk_fma_f32 v[106:107], v[38:39], v[106:107], v[110:111]
	s_add_u32 s0, s0, 0x8000
	s_addc_u32 s1, s1, 0
	global_load_dwordx2 v[2:3], v114, s[16:17]
	s_add_u32 s16, s16, 0x8000
	s_addc_u32 s17, s17, 0
	v_cvt_pk_bf16_f32 v112, v104, v105
	v_cvt_pk_bf16_f32 v113, v106, v107
	global_store_dwordx2 v114, v[112:113], s[0:1]
	ds_read_b128 v[36:39], v115 offset:2560
	s_waitcnt vmcnt(31) lgkmcnt(3)
	v_lshlrev_b32_e32 v108, 16, v4
	v_and_b32_e32 v109, 0xffff0000, v4
	v_lshlrev_b32_e32 v110, 16, v5
	v_and_b32_e32 v111, 0xffff0000, v5
	v_pk_fma_f32 v[104:105], v[40:41], v[104:105], v[108:109]
	v_pk_fma_f32 v[106:107], v[42:43], v[106:107], v[110:111]
	s_add_u32 s0, s0, 0x8000
	s_addc_u32 s1, s1, 0
	global_load_dwordx2 v[4:5], v114, s[16:17]
	s_add_u32 s16, s16, 0x8000
	s_addc_u32 s17, s17, 0
	v_cvt_pk_bf16_f32 v112, v104, v105
	v_cvt_pk_bf16_f32 v113, v106, v107
	global_store_dwordx2 v114, v[112:113], s[0:1]
	ds_read_b128 v[40:43], v115 offset:3072
	s_waitcnt vmcnt(31) lgkmcnt(3)
	v_lshlrev_b32_e32 v108, 16, v6
	v_and_b32_e32 v109, 0xffff0000, v6
	v_lshlrev_b32_e32 v110, 16, v7
	v_and_b32_e32 v111, 0xffff0000, v7
	v_pk_fma_f32 v[104:105], v[44:45], v[104:105], v[108:109]
	v_pk_fma_f32 v[106:107], v[46:47], v[106:107], v[110:111]
	s_add_u32 s0, s0, 0x8000
	s_addc_u32 s1, s1, 0
	global_load_dwordx2 v[6:7], v114, s[16:17]
	s_add_u32 s16, s16, 0x8000
	s_addc_u32 s17, s17, 0
	v_cvt_pk_bf16_f32 v112, v104, v105
	v_cvt_pk_bf16_f32 v113, v106, v107
	global_store_dwordx2 v114, v[112:113], s[0:1]
	ds_read_b128 v[44:47], v115 offset:3584
	s_waitcnt vmcnt(31) lgkmcnt(3)
	v_lshlrev_b32_e32 v108, 16, v8
	v_and_b32_e32 v109, 0xffff0000, v8
	v_lshlrev_b32_e32 v110, 16, v9
	v_and_b32_e32 v111, 0xffff0000, v9
	v_pk_fma_f32 v[104:105], v[32:33], v[104:105], v[108:109]
	v_pk_fma_f32 v[106:107], v[34:35], v[106:107], v[110:111]
	s_add_u32 s0, s0, 0x8000
	s_addc_u32 s1, s1, 0
	global_load_dwordx2 v[8:9], v114, s[16:17]
	s_add_u32 s16, s16, 0x8000
	s_addc_u32 s17, s17, 0
	v_cvt_pk_bf16_f32 v112, v104, v105
	v_cvt_pk_bf16_f32 v113, v106, v107
	global_store_dwordx2 v114, v[112:113], s[0:1]
	ds_read_b128 v[32:35], v115 offset:4096
	s_waitcnt vmcnt(31) lgkmcnt(3)
	v_lshlrev_b32_e32 v108, 16, v10
	v_and_b32_e32 v109, 0xffff0000, v10
	v_lshlrev_b32_e32 v110, 16, v11
	v_and_b32_e32 v111, 0xffff0000, v11
	v_pk_fma_f32 v[104:105], v[36:37], v[104:105], v[108:109]
	v_pk_fma_f32 v[106:107], v[38:39], v[106:107], v[110:111]
	s_add_u32 s0, s0, 0x8000
	s_addc_u32 s1, s1, 0
	global_load_dwordx2 v[10:11], v114, s[16:17]
	s_add_u32 s16, s16, 0x8000
	s_addc_u32 s17, s17, 0
	v_cvt_pk_bf16_f32 v112, v104, v105
	v_cvt_pk_bf16_f32 v113, v106, v107
	global_store_dwordx2 v114, v[112:113], s[0:1]
	ds_read_b128 v[36:39], v115 offset:4608
	s_waitcnt vmcnt(31) lgkmcnt(3)
	v_lshlrev_b32_e32 v108, 16, v12
	v_and_b32_e32 v109, 0xffff0000, v12
	v_lshlrev_b32_e32 v110, 16, v13
	v_and_b32_e32 v111, 0xffff0000, v13
	v_pk_fma_f32 v[104:105], v[40:41], v[104:105], v[108:109]
	v_pk_fma_f32 v[106:107], v[42:43], v[106:107], v[110:111]
	s_add_u32 s0, s0, 0x8000
	s_addc_u32 s1, s1, 0
	global_load_dwordx2 v[12:13], v114, s[16:17]
	s_add_u32 s16, s16, 0x8000
	s_addc_u32 s17, s17, 0
	v_cvt_pk_bf16_f32 v112, v104, v105
	v_cvt_pk_bf16_f32 v113, v106, v107
	global_store_dwordx2 v114, v[112:113], s[0:1]
	ds_read_b128 v[40:43], v115 offset:5120
	s_waitcnt vmcnt(31) lgkmcnt(3)
	v_lshlrev_b32_e32 v108, 16, v14
	v_and_b32_e32 v109, 0xffff0000, v14
	v_lshlrev_b32_e32 v110, 16, v15
	v_and_b32_e32 v111, 0xffff0000, v15
	v_pk_fma_f32 v[104:105], v[44:45], v[104:105], v[108:109]
	v_pk_fma_f32 v[106:107], v[46:47], v[106:107], v[110:111]
	s_add_u32 s0, s0, 0x8000
	s_addc_u32 s1, s1, 0
	global_load_dwordx2 v[14:15], v114, s[16:17]
	s_add_u32 s16, s16, 0x8000
	s_addc_u32 s17, s17, 0
	v_cvt_pk_bf16_f32 v112, v104, v105
	v_cvt_pk_bf16_f32 v113, v106, v107
	global_store_dwordx2 v114, v[112:113], s[0:1]
	ds_read_b128 v[44:47], v115 offset:5632
	s_waitcnt vmcnt(31) lgkmcnt(3)
	v_lshlrev_b32_e32 v108, 16, v16
	v_and_b32_e32 v109, 0xffff0000, v16
	v_lshlrev_b32_e32 v110, 16, v17
	v_and_b32_e32 v111, 0xffff0000, v17
	v_pk_fma_f32 v[104:105], v[32:33], v[104:105], v[108:109]
	v_pk_fma_f32 v[106:107], v[34:35], v[106:107], v[110:111]
	s_add_u32 s0, s0, 0x8000
	s_addc_u32 s1, s1, 0
	global_load_dwordx2 v[16:17], v114, s[16:17]
	s_add_u32 s16, s16, 0x8000
	s_addc_u32 s17, s17, 0
	v_cvt_pk_bf16_f32 v112, v104, v105
	v_cvt_pk_bf16_f32 v113, v106, v107
	global_store_dwordx2 v114, v[112:113], s[0:1]
	ds_read_b128 v[32:35], v115 offset:6144
	s_waitcnt vmcnt(31) lgkmcnt(3)
	v_lshlrev_b32_e32 v108, 16, v18
	v_and_b32_e32 v109, 0xffff0000, v18
	v_lshlrev_b32_e32 v110, 16, v19
	v_and_b32_e32 v111, 0xffff0000, v19
	v_pk_fma_f32 v[104:105], v[36:37], v[104:105], v[108:109]
	v_pk_fma_f32 v[106:107], v[38:39], v[106:107], v[110:111]
	s_add_u32 s0, s0, 0x8000
	s_addc_u32 s1, s1, 0
	global_load_dwordx2 v[18:19], v114, s[16:17]
	s_add_u32 s16, s16, 0x8000
	s_addc_u32 s17, s17, 0
	v_cvt_pk_bf16_f32 v112, v104, v105
	v_cvt_pk_bf16_f32 v113, v106, v107
	global_store_dwordx2 v114, v[112:113], s[0:1]
	ds_read_b128 v[36:39], v115 offset:6656
	s_waitcnt vmcnt(31) lgkmcnt(3)
	v_lshlrev_b32_e32 v108, 16, v20
	v_and_b32_e32 v109, 0xffff0000, v20
	v_lshlrev_b32_e32 v110, 16, v21
	v_and_b32_e32 v111, 0xffff0000, v21
	v_pk_fma_f32 v[104:105], v[40:41], v[104:105], v[108:109]
	v_pk_fma_f32 v[106:107], v[42:43], v[106:107], v[110:111]
	s_add_u32 s0, s0, 0x8000
	s_addc_u32 s1, s1, 0
	global_load_dwordx2 v[20:21], v114, s[16:17]
	s_add_u32 s16, s16, 0x8000
	s_addc_u32 s17, s17, 0
	v_cvt_pk_bf16_f32 v112, v104, v105
	v_cvt_pk_bf16_f32 v113, v106, v107
	global_store_dwordx2 v114, v[112:113], s[0:1]
	ds_read_b128 v[40:43], v115 offset:7168
	s_waitcnt vmcnt(31) lgkmcnt(3)
	v_lshlrev_b32_e32 v108, 16, v22
	v_and_b32_e32 v109, 0xffff0000, v22
	v_lshlrev_b32_e32 v110, 16, v23
	v_and_b32_e32 v111, 0xffff0000, v23
	v_pk_fma_f32 v[104:105], v[44:45], v[104:105], v[108:109]
	v_pk_fma_f32 v[106:107], v[46:47], v[106:107], v[110:111]
	s_add_u32 s0, s0, 0x8000
	s_addc_u32 s1, s1, 0
	global_load_dwordx2 v[22:23], v114, s[16:17]
	s_add_u32 s16, s16, 0x8000
	s_addc_u32 s17, s17, 0
	v_cvt_pk_bf16_f32 v112, v104, v105
	v_cvt_pk_bf16_f32 v113, v106, v107
	global_store_dwordx2 v114, v[112:113], s[0:1]
	ds_read_b128 v[44:47], v115 offset:7680
	s_waitcnt vmcnt(31) lgkmcnt(3)
	v_lshlrev_b32_e32 v108, 16, v24
	v_and_b32_e32 v109, 0xffff0000, v24
	v_lshlrev_b32_e32 v110, 16, v25
	v_and_b32_e32 v111, 0xffff0000, v25
	v_pk_fma_f32 v[104:105], v[32:33], v[104:105], v[108:109]
	v_pk_fma_f32 v[106:107], v[34:35], v[106:107], v[110:111]
	s_add_u32 s0, s0, 0x8000
	s_addc_u32 s1, s1, 0
	global_load_dwordx2 v[24:25], v114, s[16:17]
	s_add_u32 s16, s16, 0x8000
	s_addc_u32 s17, s17, 0
	v_cvt_pk_bf16_f32 v112, v104, v105
	v_cvt_pk_bf16_f32 v113, v106, v107
	global_store_dwordx2 v114, v[112:113], s[0:1]
	ds_read_b128 v[32:35], v115 offset:8192
	s_waitcnt vmcnt(31) lgkmcnt(3)
	v_lshlrev_b32_e32 v108, 16, v26
	v_and_b32_e32 v109, 0xffff0000, v26
	v_lshlrev_b32_e32 v110, 16, v27
	v_and_b32_e32 v111, 0xffff0000, v27
	v_pk_fma_f32 v[104:105], v[36:37], v[104:105], v[108:109]
	v_pk_fma_f32 v[106:107], v[38:39], v[106:107], v[110:111]
	s_add_u32 s0, s0, 0x8000
	s_addc_u32 s1, s1, 0
	global_load_dwordx2 v[26:27], v114, s[16:17]
	s_add_u32 s16, s16, 0x8000
	s_addc_u32 s17, s17, 0
	v_cvt_pk_bf16_f32 v112, v104, v105
	v_cvt_pk_bf16_f32 v113, v106, v107
	global_store_dwordx2 v114, v[112:113], s[0:1]
	ds_read_b128 v[36:39], v115 offset:8704
	s_waitcnt vmcnt(31) lgkmcnt(3)
	v_lshlrev_b32_e32 v108, 16, v28
	v_and_b32_e32 v109, 0xffff0000, v28
	v_lshlrev_b32_e32 v110, 16, v29
	v_and_b32_e32 v111, 0xffff0000, v29
	v_pk_fma_f32 v[104:105], v[40:41], v[104:105], v[108:109]
	v_pk_fma_f32 v[106:107], v[42:43], v[106:107], v[110:111]
	s_add_u32 s0, s0, 0x8000
	s_addc_u32 s1, s1, 0
	global_load_dwordx2 v[28:29], v114, s[16:17]
	s_add_u32 s16, s16, 0x8000
	s_addc_u32 s17, s17, 0
	v_cvt_pk_bf16_f32 v112, v104, v105
	v_cvt_pk_bf16_f32 v113, v106, v107
	global_store_dwordx2 v114, v[112:113], s[0:1]
	ds_read_b128 v[40:43], v115 offset:9216
	s_waitcnt vmcnt(31) lgkmcnt(3)
	v_lshlrev_b32_e32 v108, 16, v30
	v_and_b32_e32 v109, 0xffff0000, v30
	v_lshlrev_b32_e32 v110, 16, v31
	v_and_b32_e32 v111, 0xffff0000, v31
	v_pk_fma_f32 v[104:105], v[44:45], v[104:105], v[108:109]
	v_pk_fma_f32 v[106:107], v[46:47], v[106:107], v[110:111]
	s_add_u32 s0, s0, 0x8000
	s_addc_u32 s1, s1, 0
	global_load_dwordx2 v[30:31], v114, s[16:17]
	s_add_u32 s16, s16, 0x8000
	s_addc_u32 s17, s17, 0
	v_add_u32_e32 v115, 0x2000, v115
	s_add_i32 s13, s13, 1
	s_cmp_lt_u32 s13, 6
	s_cbranch_scc1 .Lhgs_loop
	v_cvt_pk_bf16_f32 v112, v104, v105
	v_cvt_pk_bf16_f32 v113, v106, v107
	global_store_dwordx2 v114, v[112:113], s[0:1]
	ds_read_b128 v[44:47], v115 offset:1536
	s_waitcnt vmcnt(31) lgkmcnt(3)
	v_lshlrev_b32_e32 v108, 16, v0
	v_and_b32_e32 v109, 0xffff0000, v0
	v_lshlrev_b32_e32 v110, 16, v1
	v_and_b32_e32 v111, 0xffff0000, v1
	v_pk_fma_f32 v[104:105], v[32:33], v[104:105], v[108:109]
	v_pk_fma_f32 v[106:107], v[34:35], v[106:107], v[110:111]
	s_add_u32 s0, s0, 0x8000
	s_addc_u32 s1, s1, 0
	v_cvt_pk_bf16_f32 v112, v104, v105
	v_cvt_pk_bf16_f32 v113, v106, v107
	global_store_dwordx2 v114, v[112:113], s[0:1]
	ds_read_b128 v[32:35], v115 offset:2048
	s_waitcnt vmcnt(30) lgkmcnt(3)
	v_lshlrev_b32_e32 v108, 16, v2
	v_and_b32_e32 v109, 0xffff0000, v2
	v_lshlrev_b32_e32 v110, 16, v3
	v_and_b32_e32 v111, 0xffff0000, v3
	v_pk_fma_f32 v[104:105], v[36:37], v[104:105], v[108:109]
	v_pk_fma_f32 v[106:107], v[38:39], v[106:107], v[110:111]
	s_add_u32 s0, s0, 0x8000
	s_addc_u32 s1, s1, 0
	v_cvt_pk_bf16_f32 v112, v104, v105
	v_cvt_pk_bf16_f32 v113, v106, v107
	global_store_dwordx2 v114, v[112:113], s[0:1]
	ds_read_b128 v[36:39], v115 offset:2560
	s_waitcnt vmcnt(29) lgkmcnt(3)
	v_lshlrev_b32_e32 v108, 16, v4
	v_and_b32_e32 v109, 0xffff0000, v4
	v_lshlrev_b32_e32 v110, 16, v5
	v_and_b32_e32 v111, 0xffff0000, v5
	v_pk_fma_f32 v[104:105], v[40:41], v[104:105], v[108:109]
	v_pk_fma_f32 v[106:107], v[42:43], v[106:107], v[110:111]
	s_add_u32 s0, s0, 0x8000
	s_addc_u32 s1, s1, 0
	v_cvt_pk_bf16_f32 v112, v104, v105
	v_cvt_pk_bf16_f32 v113, v106, v107
	global_store_dwordx2 v114, v[112:113], s[0:1]
	ds_read_b128 v[40:43], v115 offset:3072
	s_waitcnt vmcnt(28) lgkmcnt(3)
	v_lshlrev_b32_e32 v108, 16, v6
	v_and_b32_e32 v109, 0xffff0000, v6
	v_lshlrev_b32_e32 v110, 16, v7
	v_and_b32_e32 v111, 0xffff0000, v7
	v_pk_fma_f32 v[104:105], v[44:45], v[104:105], v[108:109]
	v_pk_fma_f32 v[106:107], v[46:47], v[106:107], v[110:111]
	s_add_u32 s0, s0, 0x8000
	s_addc_u32 s1, s1, 0
	v_cvt_pk_bf16_f32 v112, v104, v105
	v_cvt_pk_bf16_f32 v113, v106, v107
	global_store_dwordx2 v114, v[112:113], s[0:1]
	ds_read_b128 v[44:47], v115 offset:3584
	s_waitcnt vmcnt(27) lgkmcnt(3)
	v_lshlrev_b32_e32 v108, 16, v8
	v_and_b32_e32 v109, 0xffff0000, v8
	v_lshlrev_b32_e32 v110, 16, v9
	v_and_b32_e32 v111, 0xffff0000, v9
	v_pk_fma_f32 v[104:105], v[32:33], v[104:105], v[108:109]
	v_pk_fma_f32 v[106:107], v[34:35], v[106:107], v[110:111]
	s_add_u32 s0, s0, 0x8000
	s_addc_u32 s1, s1, 0
	v_cvt_pk_bf16_f32 v112, v104, v105
	v_cvt_pk_bf16_f32 v113, v106, v107
	global_store_dwordx2 v114, v[112:113], s[0:1]
	ds_read_b128 v[32:35], v115 offset:4096
	s_waitcnt vmcnt(26) lgkmcnt(3)
	v_lshlrev_b32_e32 v108, 16, v10
	v_and_b32_e32 v109, 0xffff0000, v10
	v_lshlrev_b32_e32 v110, 16, v11
	v_and_b32_e32 v111, 0xffff0000, v11
	v_pk_fma_f32 v[104:105], v[36:37], v[104:105], v[108:109]
	v_pk_fma_f32 v[106:107], v[38:39], v[106:107], v[110:111]
	s_add_u32 s0, s0, 0x8000
	s_addc_u32 s1, s1, 0
	v_cvt_pk_bf16_f32 v112, v104, v105
	v_cvt_pk_bf16_f32 v113, v106, v107
	global_store_dwordx2 v114, v[112:113], s[0:1]
	ds_read_b128 v[36:39], v115 offset:4608
	s_waitcnt vmcnt(25) lgkmcnt(3)
	v_lshlrev_b32_e32 v108, 16, v12
	v_and_b32_e32 v109, 0xffff0000, v12
	v_lshlrev_b32_e32 v110, 16, v13
	v_and_b32_e32 v111, 0xffff0000, v13
	v_pk_fma_f32 v[104:105], v[40:41], v[104:105], v[108:109]
	v_pk_fma_f32 v[106:107], v[42:43], v[106:107], v[110:111]
	s_add_u32 s0, s0, 0x8000
	s_addc_u32 s1, s1, 0
	v_cvt_pk_bf16_f32 v112, v104, v105
	v_cvt_pk_bf16_f32 v113, v106, v107
	global_store_dwordx2 v114, v[112:113], s[0:1]
	ds_read_b128 v[40:43], v115 offset:5120
	s_waitcnt vmcnt(24) lgkmcnt(3)
	v_lshlrev_b32_e32 v108, 16, v14
	v_and_b32_e32 v109, 0xffff0000, v14
	v_lshlrev_b32_e32 v110, 16, v15
	v_and_b32_e32 v111, 0xffff0000, v15
	v_pk_fma_f32 v[104:105], v[44:45], v[104:105], v[108:109]
	v_pk_fma_f32 v[106:107], v[46:47], v[106:107], v[110:111]
	s_add_u32 s0, s0, 0x8000
	s_addc_u32 s1, s1, 0
	v_cvt_pk_bf16_f32 v112, v104, v105
	v_cvt_pk_bf16_f32 v113, v106, v107
	global_store_dwordx2 v114, v[112:113], s[0:1]
	ds_read_b128 v[44:47], v115 offset:5632
	s_waitcnt vmcnt(23) lgkmcnt(3)
	v_lshlrev_b32_e32 v108, 16, v16
	v_and_b32_e32 v109, 0xffff0000, v16
	v_lshlrev_b32_e32 v110, 16, v17
	v_and_b32_e32 v111, 0xffff0000, v17
	v_pk_fma_f32 v[104:105], v[32:33], v[104:105], v[108:109]
	v_pk_fma_f32 v[106:107], v[34:35], v[106:107], v[110:111]
	s_add_u32 s0, s0, 0x8000
	s_addc_u32 s1, s1, 0
	v_cvt_pk_bf16_f32 v112, v104, v105
	v_cvt_pk_bf16_f32 v113, v106, v107
	global_store_dwordx2 v114, v[112:113], s[0:1]
	ds_read_b128 v[32:35], v115 offset:6144
	s_waitcnt vmcnt(22) lgkmcnt(3)
	v_lshlrev_b32_e32 v108, 16, v18
	v_and_b32_e32 v109, 0xffff0000, v18
	v_lshlrev_b32_e32 v110, 16, v19
	v_and_b32_e32 v111, 0xffff0000, v19
	v_pk_fma_f32 v[104:105], v[36:37], v[104:105], v[108:109]
	v_pk_fma_f32 v[106:107], v[38:39], v[106:107], v[110:111]
	s_add_u32 s0, s0, 0x8000
	s_addc_u32 s1, s1, 0
	v_cvt_pk_bf16_f32 v112, v104, v105
	v_cvt_pk_bf16_f32 v113, v106, v107
	global_store_dwordx2 v114, v[112:113], s[0:1]
	ds_read_b128 v[36:39], v115 offset:6656
	s_waitcnt vmcnt(21) lgkmcnt(3)
	v_lshlrev_b32_e32 v108, 16, v20
	v_and_b32_e32 v109, 0xffff0000, v20
	v_lshlrev_b32_e32 v110, 16, v21
	v_and_b32_e32 v111, 0xffff0000, v21
	v_pk_fma_f32 v[104:105], v[40:41], v[104:105], v[108:109]
	v_pk_fma_f32 v[106:107], v[42:43], v[106:107], v[110:111]
	s_add_u32 s0, s0, 0x8000
	s_addc_u32 s1, s1, 0
	v_cvt_pk_bf16_f32 v112, v104, v105
	v_cvt_pk_bf16_f32 v113, v106, v107
	global_store_dwordx2 v114, v[112:113], s[0:1]
	ds_read_b128 v[40:43], v115 offset:7168
	s_waitcnt vmcnt(20) lgkmcnt(3)
	v_lshlrev_b32_e32 v108, 16, v22
	v_and_b32_e32 v109, 0xffff0000, v22
	v_lshlrev_b32_e32 v110, 16, v23
	v_and_b32_e32 v111, 0xffff0000, v23
	v_pk_fma_f32 v[104:105], v[44:45], v[104:105], v[108:109]
	v_pk_fma_f32 v[106:107], v[46:47], v[106:107], v[110:111]
	s_add_u32 s0, s0, 0x8000
	s_addc_u32 s1, s1, 0
	v_cvt_pk_bf16_f32 v112, v104, v105
	v_cvt_pk_bf16_f32 v113, v106, v107
	global_store_dwordx2 v114, v[112:113], s[0:1]
	ds_read_b128 v[44:47], v115 offset:7680
	s_waitcnt vmcnt(19) lgkmcnt(3)
	v_lshlrev_b32_e32 v108, 16, v24
	v_and_b32_e32 v109, 0xffff0000, v24
	v_lshlrev_b32_e32 v110, 16, v25
	v_and_b32_e32 v111, 0xffff0000, v25
	v_pk_fma_f32 v[104:105], v[32:33], v[104:105], v[108:109]
	v_pk_fma_f32 v[106:107], v[34:35], v[106:107], v[110:111]
	s_add_u32 s0, s0, 0x8000
	s_addc_u32 s1, s1, 0
	v_cvt_pk_bf16_f32 v112, v104, v105
	v_cvt_pk_bf16_f32 v113, v106, v107
	global_store_dwordx2 v114, v[112:113], s[0:1]
	s_waitcnt vmcnt(18) lgkmcnt(0)
	v_lshlrev_b32_e32 v108, 16, v26
	v_and_b32_e32 v109, 0xffff0000, v26
	v_lshlrev_b32_e32 v110, 16, v27
	v_and_b32_e32 v111, 0xffff0000, v27
	v_pk_fma_f32 v[104:105], v[36:37], v[104:105], v[108:109]
	v_pk_fma_f32 v[106:107], v[38:39], v[106:107], v[110:111]
	s_add_u32 s0, s0, 0x8000
	s_addc_u32 s1, s1, 0
	v_cvt_pk_bf16_f32 v112, v104, v105
	v_cvt_pk_bf16_f32 v113, v106, v107
	global_store_dwordx2 v114, v[112:113], s[0:1]
	s_waitcnt vmcnt(17) lgkmcnt(0)
	v_lshlrev_b32_e32 v108, 16, v28
	v_and_b32_e32 v109, 0xffff0000, v28
	v_lshlrev_b32_e32 v110, 16, v29
	v_and_b32_e32 v111, 0xffff0000, v29
	v_pk_fma_f32 v[104:105], v[40:41], v[104:105], v[108:109]
	v_pk_fma_f32 v[106:107], v[42:43], v[106:107], v[110:111]
	s_add_u32 s0, s0, 0x8000
	s_addc_u32 s1, s1, 0
	v_cvt_pk_bf16_f32 v112, v104, v105
	v_cvt_pk_bf16_f32 v113, v106, v107
	global_store_dwordx2 v114, v[112:113], s[0:1]
	s_waitcnt vmcnt(16) lgkmcnt(0)
	v_lshlrev_b32_e32 v108, 16, v30
	v_and_b32_e32 v109, 0xffff0000, v30
	v_lshlrev_b32_e32 v110, 16, v31
	v_and_b32_e32 v111, 0xffff0000, v31
	v_pk_fma_f32 v[104:105], v[44:45], v[104:105], v[108:109]
	v_pk_fma_f32 v[106:107], v[46:47], v[106:107], v[110:111]
	s_add_u32 s0, s0, 0x8000
	s_addc_u32 s1, s1, 0
	v_mov_b32_e32 v68, v104
	v_mov_b32_e32 v69, v105
	v_mov_b32_e32 v70, v106
	v_mov_b32_e32 v71, v107
	s_waitcnt lgkmcnt(0)
	s_barrier
	s_branch .LBB0_986
